# PEER selection: threshold loop compares into 7 SGPR pairs (no per-compare wait states); slot positions from a per-head prefix scan instead of 7 serialized LDS atomics
# speedup vs baseline: 1.2488x; 1.0061x over previous
; #define DPP_F(v, ctrl) __int_as_float(__builtin_amdgcn_update_dpp(0, __float_as_int(v), (ctrl), 0xF, 0xF, true))
; __device__ __forceinline__ void phase5(const Params& p, char* smem, const bool store_x = true) {
;     ...
;       float m = 3.0e38f, m1 = 0.f;
; #pragma unroll 1
;       for (int rd = 0; rd < 16; rd++) {
;         float loc = NINF;
; #pragma unroll
;         for (int sl = 0; sl < 7; sl++) loc = fmaxf(loc, key[sl] < m ? key[sl] : NINF);
;         loc = fmaxf(loc, DPP_F(loc, 0xB1)); loc = fmaxf(loc, DPP_F(loc, 0x4E)); loc = fmaxf(loc, DPP_F(loc, 0x141));
;         if (rd == 0) m1 = loc;
;         m = loc;
;       }
;       float ev[7]; float es = 0.f;
; #pragma unroll
;       for (int sl = 0; sl < 7; sl++) { ev[sl] = key[sl] >= m ? __expf(key[sl] - m1) : 0.f; es += ev[sl]; }
;       es += DPP_F(es, 0xB1); es += DPP_F(es, 0x4E); es += DPP_F(es, 0x141);
;       const float inv = 1.f / es;
; #pragma unroll
;       for (int sl = 0; sl < 7; sl++) {
;         if (key[sl] >= m) {
;           int pos = atomicAdd(&wcnt[hd], 1);
;           int ia = ti[ij[sl] >> 4], ib = ti[16 + (ij[sl] & 15)];
;           widx[hd * 16 + pos] = ia * 128 + ib;
;           wgate[hd * 16 + pos] = ev[sl] * inv;
;         }
;       }
.LBB0_1487:
	v_cmp_gt_f32_e64 s[18:19], v54, v52
	v_cmp_lt_f32_e64 s[20:21], v48, v54
	v_cmp_lt_f32_e64 s[22:23], v51, v54
	v_cmp_lt_f32_e64 s[24:25], v32, v54
	v_cmp_lt_f32_e64 s[26:27], v33, v54
	v_cmp_lt_f32_e64 s[28:29], v49, v54
	v_cmp_lt_f32_e64 s[36:37], v50, v54
	s_cmp_eq_u32 s0, 16
	v_mov_b32_e32 v56, v55
	v_cndmask_b32_e64 v0, v252, v53, s[18:19]
	v_cndmask_b32_e64 v1, v252, v48, s[20:21]
	v_cndmask_b32_e64 v2, v252, v51, s[22:23]
	v_cndmask_b32_e64 v3, v252, v32, s[24:25]
	v_cndmask_b32_e64 v4, v252, v33, s[26:27]
	v_cndmask_b32_e64 v5, v252, v49, s[28:29]
	v_cndmask_b32_e64 v6, v252, v50, s[36:37]
	v_max3_f32 v0, v0, v1, v2
	v_max3_f32 v3, v3, v4, v5
	s_cselect_b64 vcc, -1, 0
	s_add_i32 s0, s0, -1
	v_max3_f32 v0, v0, v3, v6
	s_cmp_lg_u32 s0, 0
	s_nop 0
	v_mov_b32_dpp v1, v0 quad_perm:[1,0,3,2] row_mask:0xf bank_mask:0xf bound_ctrl:1
	v_max_f32_e32 v1, v1, v1
	v_max_f32_e32 v0, v0, v1
	s_nop 1
	v_mov_b32_dpp v1, v0 quad_perm:[2,3,0,1] row_mask:0xf bank_mask:0xf bound_ctrl:1
	v_max_f32_e32 v1, v1, v1
	v_max_f32_e32 v0, v0, v1
	s_nop 1
	v_mov_b32_dpp v1, v0 row_half_mirror row_mask:0xf bank_mask:0xf bound_ctrl:1
	v_max_f32_e32 v1, v1, v1
	v_max_f32_e32 v54, v0, v1
	v_cndmask_b32_e32 v55, v56, v54, vcc
	s_cbranch_scc1 .LBB0_1487
	v_sub_f32_e32 v0, v52, v56
	v_mul_f32_e32 v0, 0x3fb8aa3b, v0
	v_exp_f32_e32 v55, v0
	v_sub_f32_e32 v0, v48, v56
	v_mul_f32_e32 v0, 0x3fb8aa3b, v0
	v_exp_f32_e32 v53, v0
	v_sub_f32_e32 v0, v51, v56
	v_mul_f32_e32 v0, 0x3fb8aa3b, v0
	v_cmp_le_f32_e64 s[28:29], v54, v52
	v_exp_f32_e32 v52, v0
	v_add_f32_e32 v1, 0, v55
	v_cmp_ge_f32_e64 s[26:27], v48, v54
	v_cndmask_b32_e64 v1, 0, v1, s[28:29]
	v_cmp_ge_f32_e64 s[24:25], v51, v54
	v_cndmask_b32_e64 v0, 0, v53, s[26:27]
	v_add_f32_e32 v0, v1, v0
	v_cndmask_b32_e64 v1, 0, v52, s[24:25]
	v_add_f32_e32 v0, v1, v0
	v_sub_f32_e32 v1, v32, v56
	v_mul_f32_e32 v1, 0x3fb8aa3b, v1
	v_exp_f32_e32 v51, v1
	v_sub_f32_e32 v1, v33, v56
	v_mul_f32_e32 v1, 0x3fb8aa3b, v1
	v_exp_f32_e32 v48, v1
	v_cmp_ge_f32_e64 s[22:23], v32, v54
	v_cmp_ge_f32_e64 s[20:21], v33, v54
	v_cmp_ge_f32_e64 s[18:19], v49, v54
	v_cndmask_b32_e64 v1, 0, v51, s[22:23]
	v_add_f32_e32 v0, v1, v0
	v_cndmask_b32_e64 v1, 0, v48, s[20:21]
	v_add_f32_e32 v0, v1, v0
	v_sub_f32_e32 v1, v49, v56
	v_mul_f32_e32 v1, 0x3fb8aa3b, v1
	v_exp_f32_e32 v33, v1
	v_sub_f32_e32 v1, v50, v56
	v_mul_f32_e32 v1, 0x3fb8aa3b, v1
	v_exp_f32_e32 v32, v1
	v_cndmask_b32_e64 v1, 0, v33, s[18:19]
	v_cmp_ge_f32_e64 s[0:1], v50, v54
	v_add_f32_e32 v0, v1, v0
	s_nop 0
	v_cndmask_b32_e64 v1, 0, v32, s[0:1]
	v_add_f32_e32 v0, v1, v0
	s_nop 1
	v_add_f32_dpp v0, v0, v0 quad_perm:[1,0,3,2] row_mask:0xf bank_mask:0xf bound_ctrl:1
	s_nop 1
	v_add_f32_dpp v0, v0, v0 quad_perm:[2,3,0,1] row_mask:0xf bank_mask:0xf bound_ctrl:1
	s_nop 1
	v_add_f32_dpp v0, v0, v0 row_half_mirror row_mask:0xf bank_mask:0xf bound_ctrl:1
	v_div_scale_f32 v1, s[36:37], v0, v0, 1.0
	v_rcp_f32_e32 v2, v1
	s_nop 0
	v_fma_f32 v3, -v1, v2, 1.0
	v_fmac_f32_e32 v2, v3, v2
	v_div_scale_f32 v3, vcc, 1.0, v0, 1.0
	v_mul_f32_e32 v4, v3, v2
	v_fma_f32 v5, -v1, v4, v3
	v_fmac_f32_e32 v4, v5, v2
	v_fma_f32 v1, -v1, v4, v3
	v_div_fmas_f32 v1, v1, v2, v4
	v_div_fixup_f32 v49, v1, v0, 1.0
	v_cndmask_b32_e64 v0, 0, 1, s[28:29]
	v_cndmask_b32_e64 v1, 0, 1, s[26:27]
	v_cndmask_b32_e64 v2, 0, 1, s[24:25]
	v_cndmask_b32_e64 v3, 0, 1, s[22:23]
	v_cndmask_b32_e64 v4, 0, 1, s[20:21]
	v_cndmask_b32_e64 v5, 0, 1, s[18:19]
	v_cndmask_b32_e64 v6, 0, 1, s[0:1]
	ds_read_b32 v10, v46 offset:3072
	ds_read_b32 v11, v47 offset:3136
	ds_read_b32 v12, v44 offset:3072
	ds_read_b32 v13, v45 offset:3136
	ds_read_b32 v14, v42 offset:3072
	ds_read_b32 v15, v43 offset:3136
	ds_read_b32 v16, v40 offset:3072
	ds_read_b32 v17, v41 offset:3136
	ds_read_b32 v18, v38 offset:3072
	ds_read_b32 v19, v39 offset:3136
	ds_read_b32 v20, v36 offset:3072
	ds_read_b32 v21, v37 offset:3136
	ds_read_b32 v22, v34 offset:3072
	ds_read_b32 v23, v35 offset:3136
	v_add_u32_e32 v24, v0, v1
	v_add_u32_e32 v25, v24, v2
	v_add_u32_e32 v26, v25, v3
	v_add_u32_e32 v27, v26, v4
	v_add_u32_e32 v28, v27, v5
	v_add_u32_e32 v8, v28, v6
	s_mov_b32 s38, 0xfefefefe
	s_mov_b32 s39, 0xfefefefe
	s_mov_b32 s40, 0xfcfcfcfc
	s_mov_b32 s41, 0xfcfcfcfc
	s_mov_b32 s42, 0xf0f0f0f0
	s_mov_b32 s43, 0xf0f0f0f0
	v_mov_b32_dpp v9, v8 row_shr:1 row_mask:0xf bank_mask:0xf bound_ctrl:1
	v_cndmask_b32_e64 v9, 0, v9, s[38:39]
	v_add_u32_e32 v7, v8, v9
	s_nop 1
	v_mov_b32_dpp v9, v7 row_shr:2 row_mask:0xf bank_mask:0xf bound_ctrl:1
	v_cndmask_b32_e64 v9, 0, v9, s[40:41]
	v_add_u32_e32 v7, v7, v9
	s_nop 1
	v_mov_b32_dpp v9, v7 row_shr:4 row_mask:0xf bank_mask:0xf bound_ctrl:1
	v_cndmask_b32_e64 v9, 0, v9, s[42:43]
	v_add_u32_e32 v7, v7, v9
	v_sub_u32_e32 v7, v7, v8
	v_add_u32_e32 v7, v7, v239
	v_lshl_add_u32 v29, v7, 2, v176
	v_add_u32_e32 v9, v7, v0
	v_lshl_add_u32 v30, v9, 2, v176
	v_add_u32_e32 v9, v7, v24
	v_lshl_add_u32 v31, v9, 2, v176
	v_add_u32_e32 v9, v7, v25
	v_lshl_add_u32 v56, v9, 2, v176
	v_add_u32_e32 v9, v7, v26
	v_lshl_add_u32 v57, v9, 2, v176
	v_add_u32_e32 v9, v7, v27
	v_lshl_add_u32 v58, v9, 2, v176
	v_add_u32_e32 v9, v7, v28
	v_lshl_add_u32 v59, v9, 2, v176
	s_waitcnt lgkmcnt(0)
	v_lshl_add_u32 v10, v10, 7, v11
	v_mul_f32_e32 v11, v55, v49
	v_lshl_add_u32 v12, v12, 7, v13
	v_mul_f32_e32 v13, v53, v49
	v_lshl_add_u32 v14, v14, 7, v15
	v_mul_f32_e32 v15, v52, v49
	v_lshl_add_u32 v16, v16, 7, v17
	v_mul_f32_e32 v17, v51, v49
	v_lshl_add_u32 v18, v18, 7, v19
	v_mul_f32_e32 v19, v48, v49
	v_lshl_add_u32 v20, v20, 7, v21
	v_mul_f32_e32 v21, v33, v49
	v_lshl_add_u32 v22, v22, 7, v23
	v_mul_f32_e32 v23, v32, v49
	s_mov_b64 exec, s[28:29]
	ds_write2st64_b32 v29, v10, v11 offset1:2
	s_mov_b64 exec, s[26:27]
	ds_write2st64_b32 v30, v12, v13 offset1:2
	s_mov_b64 exec, s[24:25]
	ds_write2st64_b32 v31, v14, v15 offset1:2
	s_mov_b64 exec, s[22:23]
	ds_write2st64_b32 v56, v16, v17 offset1:2
	s_mov_b64 exec, s[20:21]
	ds_write2st64_b32 v57, v18, v19 offset1:2
	s_mov_b64 exec, s[18:19]
	ds_write2st64_b32 v58, v20, v21 offset1:2
	s_mov_b64 exec, s[0:1]
	ds_write2st64_b32 v59, v22, v23 offset1:2
	s_mov_b64 exec, -1
.LBB0_1496:
	s_or_b64 exec, exec, s[18:19]
	v_mbcnt_lo_u32_b32 v0, -1, 0
	v_mbcnt_hi_u32_b32 v0, -1, v0
	v_lshl_add_u32 v1, v0, 3, v176
	ds_read_b64 v[2:3], v1
	ds_read_b64 v[4:5], v1 offset:512
	s_add_u32 s98, s80, 0x3bb5000
	s_addc_u32 s99, s81, 0
	v_lshl_add_u32 v6, v0, 3, v200
	v_lshrrev_b32_e32 v7, 8, v200
	v_add_u32_e32 v7, 0x1100000, v7
	v_mov_b32_e32 v20, 0
	s_waitcnt lgkmcnt(0)
	v_lshlrev_b32_e32 v16, 7, v2
	v_lshlrev_b32_e32 v17, 7, v3
	global_store_dwordx2 v6, v[16:17], s[98:99]
	global_store_dwordx2 v6, v[4:5], s[98:99] offset:512
	s_mov_b64 exec, 1
	global_store_dword v7, v20, s[98:99]
	s_mov_b64 exec, -1
	s_waitcnt vmcnt(3)
	s_and_b64 vcc, exec, s[34:35]
	s_cbranch_vccnz .Lp5a_done
	s_branch .LBB0_1482
.Lp5a_done:
.Lpb1_1523:
	s_waitcnt vmcnt(0)
	s_barrier
	s_and_saveexec_b64 s[0:1], s[72:73]
	s_cbranch_execz .Lpb1_1575

; __device__ __forceinline__ void xcd_barrier(const XcdBarrier& b) {
;     ...
;         unsigned nloc = b.st[0], nx = b.st[1];
;         if (nloc == 0u) { xcd_barrier_complete(bar, b.x, nloc, nx); b.st[0] = nloc; b.st[1] = nx; }
	v_mov_b32_e32 v0, 0x23800
	s_waitcnt vmcnt(0) expcnt(0) lgkmcnt(0)
	ds_read_b32 v2, v0
	v_mov_b32_e32 v0, 0x23804
	ds_read_b32 v0, v0
	s_waitcnt lgkmcnt(1)
	v_cmp_ne_u32_e32 vcc, 0, v2
	s_cbranch_vccnz .Lpb1_1539

; __device__ __forceinline__ unsigned xb_ld(unsigned* p)              { return __hip_atomic_load(p, __ATOMIC_RELAXED, __HIP_MEMORY_SCOPE_AGENT); }
; __device__ __forceinline__ void xcd_barrier_complete(unsigned* bar, unsigned x, unsigned& nloc, unsigned& nx) {
;     const unsigned G = gridDim.x * gridDim.y * gridDim.z;
;     unsigned sum, cnt, mine, sp = 0u;
;     for (;;) {
;         sum = 0u; cnt = 0u; mine = 0u;
; #pragma unroll
;         for (unsigned j = 0; j < 16; ++j) { const unsigned c = xb_ld(&bar[XB_XCNT(j)]); sum += c; cnt += (c > 0u) ? 1u : 0u; mine = (j == x) ? c : mine; }
;         if (sum == G) break;
	v_readlane_b32 s4, v254, 0
	s_mul_i32 s33, s83, s4
	s_add_u32 s4, s80, 0x12f35200
	s_addc_u32 s5, s81, 0
	s_add_u32 s6, s80, 0x12f35400
	s_addc_u32 s7, s81, 0
	s_add_u32 s8, s80, 0x12f35500
	s_addc_u32 s9, s81, 0
	s_add_u32 s10, s80, 0x12f35600
	s_addc_u32 s11, s81, 0
	s_add_u32 s12, s80, 0x12f35700
	s_addc_u32 s13, s81, 0
	s_add_u32 s14, s80, 0x12f35800
	s_addc_u32 s15, s81, 0
	s_add_u32 s16, s80, 0x12f35900
	s_addc_u32 s17, s81, 0
	s_add_u32 s18, s80, 0x12f35a00
	s_addc_u32 s19, s81, 0
	s_add_u32 s20, s80, 0x12f35b00
	s_addc_u32 s21, s81, 0
	s_add_u32 s22, s80, 0x12f35c00
	s_addc_u32 s23, s81, 0
	s_add_u32 s24, s80, 0x12f35d00
	s_addc_u32 s25, s81, 0
	s_add_u32 s26, s80, 0x12f35e00
	s_addc_u32 s27, s81, 0
	s_add_u32 s28, s80, 0x12f35f00
	s_addc_u32 s29, s81, 0
	s_add_u32 s34, s80, 0x12f36000
	s_addc_u32 s35, s81, 0
	s_add_u32 s36, s80, 0x12f36100
	s_addc_u32 s37, s81, 0
	s_add_u32 s38, s80, 0x12f36200
	s_addc_u32 s39, s81, 0
	s_add_u32 s40, s80, 0x12f36300
	s_mul_i32 s33, s33, s82
	s_addc_u32 s41, s81, 0
	s_mov_b32 s48, 1
	v_mov_b32_e32 v16, 0
	s_branch .Lpb1_1527
